# RWKV unit prologue: LoRA-weight staging loop unrolled (both global loads issued before the first wait) - prologue de-serialisation
# speedup vs baseline: 1.0017x; 1.0017x over previous
.LBB0_348:
	v_ashrrev_i32_e32 v5, 9, v4
	v_add_u32_e32 v6, v5, v0
	v_mul_i32_i24_e32 v6, 12, v6
	v_ashrrev_i32_e32 v7, 31, v6
	v_lshl_add_u64 v[6:7], v[6:7], 0, v[108:109]
	s_waitcnt vmcnt(22)
	v_bfe_u32 v10, v4, 3, 6
	v_lshlrev_b64 v[6:7], 13, v[6:7]
	v_lshlrev_b32_e32 v8, 1, v1
	v_lshlrev_b32_e32 v2, 7, v10
	v_lshl_add_u64 v[6:7], s[22:23], 0, v[6:7]
	v_lshl_add_u64 v[6:7], v[6:7], 0, v[2:3]
	v_and_b32_e32 v2, 0x70, v8
	v_lshl_add_u64 v[6:7], v[6:7], 0, v[2:3]
	global_load_dwordx4 v[6:9], v[6:7], off
	v_lshl_or_b32 v5, v5, 6, v10
	v_add_u32_e32 v11, 0x200, v4
	v_cmp_lt_i32_e32 vcc, s90, v4
	v_mul_lo_u32 v5, v5, s92
	v_add_u32_e32 v1, 0x1000, v1
	s_or_b64 s[4:5], vcc, s[4:5]
	v_mov_b32_e32 v4, v11
	v_add3_u32 v249, 0, v5, v2
	v_ashrrev_i32_e32 v5, 9, v4
	v_add_u32_e32 v244, v5, v0
	v_mul_i32_i24_e32 v244, 12, v244
	v_ashrrev_i32_e32 v245, 31, v244
	v_lshl_add_u64 v[244:245], v[244:245], 0, v[108:109]
	s_waitcnt vmcnt(22)
	v_bfe_u32 v10, v4, 3, 6
	v_lshlrev_b64 v[244:245], 13, v[244:245]
	v_lshlrev_b32_e32 v246, 1, v1
	v_lshlrev_b32_e32 v2, 7, v10
	v_lshl_add_u64 v[244:245], s[22:23], 0, v[244:245]
	v_lshl_add_u64 v[244:245], v[244:245], 0, v[2:3]
	v_and_b32_e32 v2, 0x70, v246
	v_lshl_add_u64 v[244:245], v[244:245], 0, v[2:3]
	global_load_dwordx4 v[244:247], v[244:245], off
	v_lshl_or_b32 v5, v5, 6, v10
	v_add_u32_e32 v11, 0x200, v4
	v_cmp_lt_i32_e32 vcc, s90, v4
	v_mul_lo_u32 v5, v5, s92
	v_add_u32_e32 v1, 0x1000, v1
	s_or_b64 s[4:5], vcc, s[4:5]
	v_mov_b32_e32 v4, v11
	v_add3_u32 v248, 0, v5, v2
	s_waitcnt vmcnt(1)
	ds_write_b128 v249, v[6:9] offset:57344
	s_waitcnt vmcnt(0)
	ds_write_b128 v248, v[244:247] offset:57344

.LBB0_445:
	v_ashrrev_i32_e32 v30, 9, v25
	v_add_u32_e32 v26, v30, v23
	v_mad_i32_i24 v26, v26, 12, v0
	v_ashrrev_i32_e32 v27, 31, v26
	v_bfe_u32 v31, v25, 3, 6
	v_lshlrev_b64 v[26:27], 13, v[26:27]
	v_lshlrev_b32_e32 v28, 1, v24
	v_lshlrev_b32_e32 v2, 7, v31
	v_lshl_add_u64 v[26:27], s[66:67], 0, v[26:27]
	v_lshl_add_u64 v[26:27], v[26:27], 0, v[2:3]
	v_and_b32_e32 v2, 0x70, v28
	v_lshl_add_u64 v[26:27], v[26:27], 0, v[2:3]
	global_load_dwordx4 v[26:29], v[26:27], off
	v_lshl_or_b32 v30, v30, 6, v31
	s_waitcnt vmcnt(5)
	v_add_u32_e32 v32, 0x200, v25
	v_cmp_lt_i32_e32 vcc, s90, v25
	v_mul_lo_u32 v30, v30, s92
	v_add_u32_e32 v24, 0x1000, v24
	s_or_b64 s[4:5], vcc, s[4:5]
	v_mov_b32_e32 v25, v32
	v_add3_u32 v249, 0, v30, v2
	v_ashrrev_i32_e32 v30, 9, v25
	v_add_u32_e32 v244, v30, v23
	v_mad_i32_i24 v244, v244, 12, v0
	v_ashrrev_i32_e32 v245, 31, v244
	v_bfe_u32 v31, v25, 3, 6
	v_lshlrev_b64 v[244:245], 13, v[244:245]
	v_lshlrev_b32_e32 v246, 1, v24
	v_lshlrev_b32_e32 v2, 7, v31
	v_lshl_add_u64 v[244:245], s[66:67], 0, v[244:245]
	v_lshl_add_u64 v[244:245], v[244:245], 0, v[2:3]
	v_and_b32_e32 v2, 0x70, v246
	v_lshl_add_u64 v[244:245], v[244:245], 0, v[2:3]
	global_load_dwordx4 v[244:247], v[244:245], off
	v_lshl_or_b32 v30, v30, 6, v31
	s_waitcnt vmcnt(5)
	v_add_u32_e32 v32, 0x200, v25
	v_cmp_lt_i32_e32 vcc, s90, v25
	v_mul_lo_u32 v30, v30, s92
	v_add_u32_e32 v24, 0x1000, v24
	s_or_b64 s[4:5], vcc, s[4:5]
	v_mov_b32_e32 v25, v32
	v_add3_u32 v248, 0, v30, v2
	s_waitcnt vmcnt(1)
	ds_write_b128 v249, v[26:29] offset:57344
	s_waitcnt vmcnt(0)
	ds_write_b128 v248, v[244:247] offset:57344

.LBB0_921:
	v_ashrrev_i32_e32 v5, 9, v4
	v_add_u32_e32 v6, v0, v5
	v_mul_i32_i24_e32 v6, 12, v6
	v_ashrrev_i32_e32 v7, 31, v6
	v_lshl_add_u64 v[6:7], v[6:7], 0, v[108:109]
	s_waitcnt vmcnt(22)
	v_bfe_u32 v10, v4, 3, 6
	v_lshlrev_b64 v[6:7], 13, v[6:7]
	v_lshlrev_b32_e32 v8, 1, v1
	v_lshlrev_b32_e32 v2, 7, v10
	v_lshl_add_u64 v[6:7], s[22:23], 0, v[6:7]
	v_lshl_add_u64 v[6:7], v[6:7], 0, v[2:3]
	v_and_b32_e32 v2, 0x70, v8
	v_lshl_add_u64 v[6:7], v[6:7], 0, v[2:3]
	global_load_dwordx4 v[6:9], v[6:7], off
	v_lshl_or_b32 v5, v5, 6, v10
	v_add_u32_e32 v11, 0x200, v4
	v_cmp_lt_i32_e32 vcc, s83, v4
	v_mul_lo_u32 v5, v5, s89
	v_add_u32_e32 v1, 0x1000, v1
	s_or_b64 s[4:5], vcc, s[4:5]
	v_mov_b32_e32 v4, v11
	v_add3_u32 v249, 0, v5, v2
	v_ashrrev_i32_e32 v5, 9, v4
	v_add_u32_e32 v244, v0, v5
	v_mul_i32_i24_e32 v244, 12, v244
	v_ashrrev_i32_e32 v245, 31, v244
	v_lshl_add_u64 v[244:245], v[244:245], 0, v[108:109]
	s_waitcnt vmcnt(22)
	v_bfe_u32 v10, v4, 3, 6
	v_lshlrev_b64 v[244:245], 13, v[244:245]
	v_lshlrev_b32_e32 v246, 1, v1
	v_lshlrev_b32_e32 v2, 7, v10
	v_lshl_add_u64 v[244:245], s[22:23], 0, v[244:245]
	v_lshl_add_u64 v[244:245], v[244:245], 0, v[2:3]
	v_and_b32_e32 v2, 0x70, v246
	v_lshl_add_u64 v[244:245], v[244:245], 0, v[2:3]
	global_load_dwordx4 v[244:247], v[244:245], off
	v_lshl_or_b32 v5, v5, 6, v10
	v_add_u32_e32 v11, 0x200, v4
	v_cmp_lt_i32_e32 vcc, s83, v4
	v_mul_lo_u32 v5, v5, s89
	v_add_u32_e32 v1, 0x1000, v1
	s_or_b64 s[4:5], vcc, s[4:5]
	v_mov_b32_e32 v4, v11
	v_add3_u32 v248, 0, v5, v2
	s_waitcnt vmcnt(1)
	ds_write_b128 v249, v[6:9] offset:57344
	s_waitcnt vmcnt(0)
	ds_write_b128 v248, v[244:247] offset:57344

.LBB0_1018:
	v_ashrrev_i32_e32 v25, 9, v24
	v_add_u32_e32 v26, v22, v25
	v_mad_i32_i24 v26, v26, 12, v0
	v_ashrrev_i32_e32 v27, 31, v26
	v_bfe_u32 v30, v24, 3, 6
	v_lshlrev_b64 v[26:27], 13, v[26:27]
	v_lshlrev_b32_e32 v28, 1, v23
	v_lshlrev_b32_e32 v2, 7, v30
	v_lshl_add_u64 v[26:27], s[66:67], 0, v[26:27]
	v_lshl_add_u64 v[26:27], v[26:27], 0, v[2:3]
	v_and_b32_e32 v2, 0x70, v28
	v_lshl_add_u64 v[26:27], v[26:27], 0, v[2:3]
	global_load_dwordx4 v[26:29], v[26:27], off
	v_lshl_or_b32 v25, v25, 6, v30
	v_add_u32_e32 v31, 0x200, v24
	v_cmp_lt_i32_e32 vcc, s83, v24
	v_mul_lo_u32 v25, v25, s89
	v_add_u32_e32 v23, 0x1000, v23
	s_or_b64 s[4:5], vcc, s[4:5]
	v_mov_b32_e32 v24, v31
	v_add3_u32 v249, 0, v25, v2
	v_ashrrev_i32_e32 v25, 9, v24
	v_add_u32_e32 v244, v22, v25
	v_mad_i32_i24 v244, v244, 12, v0
	v_ashrrev_i32_e32 v245, 31, v244
	v_bfe_u32 v30, v24, 3, 6
	v_lshlrev_b64 v[244:245], 13, v[244:245]
	v_lshlrev_b32_e32 v246, 1, v23
	v_lshlrev_b32_e32 v2, 7, v30
	v_lshl_add_u64 v[244:245], s[66:67], 0, v[244:245]
	v_lshl_add_u64 v[244:245], v[244:245], 0, v[2:3]
	v_and_b32_e32 v2, 0x70, v246
	v_lshl_add_u64 v[244:245], v[244:245], 0, v[2:3]
	global_load_dwordx4 v[244:247], v[244:245], off
	v_lshl_or_b32 v25, v25, 6, v30
	v_add_u32_e32 v31, 0x200, v24
	v_cmp_lt_i32_e32 vcc, s83, v24
	v_mul_lo_u32 v25, v25, s89
	v_add_u32_e32 v23, 0x1000, v23
	s_or_b64 s[4:5], vcc, s[4:5]
	v_mov_b32_e32 v24, v31
	v_add3_u32 v248, 0, v25, v2
	s_waitcnt vmcnt(1)
	ds_write_b128 v249, v[26:29] offset:57344
	s_waitcnt vmcnt(0)
	ds_write_b128 v248, v[244:247] offset:57344
